# sgemm_sample v2 (k3,k6,k10,k13): W slice staged once per workgroup into LDS via LDS-DMA in fragment order, A fragments fully prefetched: one round trip, 2.4x fewer global loads
# speedup vs baseline: 1.0173x; 1.0101x over previous
_Z10fwd_kernelILi3ELi4EEv4Args:
	v_mov_b32_e32 v1, v0
	s_load_dword s3, s[0:1], 0xe8
	s_load_dwordx2 s[0:1], s[0:1], 0xd8
	v_readfirstlane_b32 s4, v1
	s_ashr_i32 s4, s4, 6
	s_waitcnt lgkmcnt(0)
	s_add_u32 s6, s0, 0x700000
	s_addc_u32 s7, s1, 0
	s_add_u32 s20, s0, 0xf700000
	s_addc_u32 s21, s1, 0
	s_add_u32 s22, s0, 0x7400000
	s_addc_u32 s23, s1, 0
	v_readfirstlane_b32 s24, v0
	s_lshr_b32 s24, s24, 6
	v_and_b32_e32 v185, 31, v0
	v_bfe_u32 v186, v0, 5, 1
	v_and_b32_e32 v187, 63, v0
	v_lshlrev_b32_e32 v182, 11, v185
	v_lshl_add_u32 v182, v186, 4, v182
	v_lshlrev_b32_e32 v183, 2, v185
	v_lshl_add_u32 v183, v186, 14, v183
	v_lshlrev_b32_e32 v184, 4, v187
	s_mov_b32 s25, s2
	s_cmpk_gt_u32 s25, 0xff
	s_cbranch_scc1 .Lsg3_done
.Lsg3_wg:
	s_and_b32 s26, s25, 7
	s_lshr_b32 s27, s25, 3
	s_lshl_b32 s28, s26, 1
	s_lshr_b32 s29, s27, 4
	s_add_u32 s28, s28, s29
	s_bfe_u32 s29, s27, 0x10003
	s_and_b32 s30, s27, 7
	s_lshl_b32 s31, s24, 3
	s_add_u32 s30, s30, s31
	s_lshl_b32 s31, s29, 10
	s_lshl_b32 s33, s28, 17
	s_add_u32 s33, s33, s31
	s_lshl_b32 s34, s24, 7
	s_add_u32 s33, s33, s34
	s_add_u32 s36, s6, s33
	s_addc_u32 s37, s7, 0
	v_mov_b32_e32 v179, v182
	v_add_u32_e32 v180, 0x10000, v182
	s_lshl_b32 s33, s30, 16
	s_add_u32 s33, s33, s31
	v_add_u32_e32 v178, s33, v182
	s_lshl_b32 s33, s29, 21
	s_lshl_b32 s34, s30, 17
	s_add_u32 s33, s33, s34
	s_lshl_b32 s34, s28, 8
	s_add_u32 s33, s33, s34
	v_add_u32_e32 v181, s33, v183
	s_lshl_b32 s35, s24, 13
	s_cmp_lt_u32 s24, 2
	s_cbranch_scc0 .Lsg3_wonly
	s_add_i32 m0, s35, 0x0
	global_load_dwordx4 v[34:37], v178, s[20:21] offset:0
	global_load_dwordx4 v[38:41], v178, s[20:21] offset:32
	global_load_dwordx4 v[42:45], v178, s[20:21] offset:64
	global_load_dwordx4 v[46:49], v178, s[20:21] offset:96
	global_load_lds_dwordx4 v179, s[36:37]
	s_add_i32 m0, s35, 0x400
	global_load_dwordx4 v[50:53], v178, s[20:21] offset:128
	global_load_dwordx4 v[54:57], v178, s[20:21] offset:160
	global_load_dwordx4 v[58:61], v178, s[20:21] offset:192
	global_load_dwordx4 v[62:65], v178, s[20:21] offset:224
	global_load_lds_dwordx4 v180, s[36:37]
	s_add_u32 s36, s36, 32
	s_addc_u32 s37, s37, 0
	s_add_i32 m0, s35, 0x800
	global_load_dwordx4 v[66:69], v178, s[20:21] offset:256
	global_load_dwordx4 v[70:73], v178, s[20:21] offset:288
	global_load_dwordx4 v[74:77], v178, s[20:21] offset:320
	global_load_dwordx4 v[78:81], v178, s[20:21] offset:352
	global_load_lds_dwordx4 v179, s[36:37]
	s_add_i32 m0, s35, 0xc00
	global_load_dwordx4 v[82:85], v178, s[20:21] offset:384
	global_load_dwordx4 v[86:89], v178, s[20:21] offset:416
	global_load_dwordx4 v[90:93], v178, s[20:21] offset:448
	global_load_dwordx4 v[94:97], v178, s[20:21] offset:480
	global_load_lds_dwordx4 v180, s[36:37]
	s_add_u32 s36, s36, 32
	s_addc_u32 s37, s37, 0
	s_add_i32 m0, s35, 0x1000
	global_load_dwordx4 v[98:101], v178, s[20:21] offset:512
	global_load_dwordx4 v[102:105], v178, s[20:21] offset:544
	global_load_dwordx4 v[106:109], v178, s[20:21] offset:576
	global_load_dwordx4 v[110:113], v178, s[20:21] offset:608
	global_load_lds_dwordx4 v179, s[36:37]
	s_add_i32 m0, s35, 0x1400
	global_load_dwordx4 v[114:117], v178, s[20:21] offset:640
	global_load_dwordx4 v[118:121], v178, s[20:21] offset:672
	global_load_dwordx4 v[122:125], v178, s[20:21] offset:704
	global_load_dwordx4 v[126:129], v178, s[20:21] offset:736
	global_load_lds_dwordx4 v180, s[36:37]
	s_add_u32 s36, s36, 32
	s_addc_u32 s37, s37, 0
	s_add_i32 m0, s35, 0x1800
	global_load_dwordx4 v[130:133], v178, s[20:21] offset:768
	global_load_dwordx4 v[134:137], v178, s[20:21] offset:800
	global_load_dwordx4 v[138:141], v178, s[20:21] offset:832
	global_load_dwordx4 v[142:145], v178, s[20:21] offset:864
	global_load_lds_dwordx4 v179, s[36:37]
	s_add_i32 m0, s35, 0x1c00
	global_load_dwordx4 v[146:149], v178, s[20:21] offset:896
	global_load_dwordx4 v[150:153], v178, s[20:21] offset:928
	global_load_dwordx4 v[154:157], v178, s[20:21] offset:960
	global_load_dwordx4 v[158:161], v178, s[20:21] offset:992
	global_load_lds_dwordx4 v180, s[36:37]
	s_branch .Lsg3_issued
.Lsg3_wonly:
	s_add_i32 m0, s35, 0x0
	s_nop 0
	global_load_lds_dwordx4 v179, s[36:37]
	s_add_i32 m0, s35, 0x400
	s_nop 0
	global_load_lds_dwordx4 v180, s[36:37]
	s_add_u32 s36, s36, 32
	s_addc_u32 s37, s37, 0
	s_add_i32 m0, s35, 0x800
	s_nop 0
	global_load_lds_dwordx4 v179, s[36:37]
	s_add_i32 m0, s35, 0xc00
	s_nop 0
	global_load_lds_dwordx4 v180, s[36:37]
	s_add_u32 s36, s36, 32
	s_addc_u32 s37, s37, 0
	s_add_i32 m0, s35, 0x1000
	s_nop 0
	global_load_lds_dwordx4 v179, s[36:37]
	s_add_i32 m0, s35, 0x1400
	s_nop 0
	global_load_lds_dwordx4 v180, s[36:37]
	s_add_u32 s36, s36, 32
	s_addc_u32 s37, s37, 0
	s_add_i32 m0, s35, 0x1800
	s_nop 0
	global_load_lds_dwordx4 v179, s[36:37]
	s_add_i32 m0, s35, 0x1c00
	s_nop 0
	global_load_lds_dwordx4 v180, s[36:37]
.Lsg3_issued:
	s_waitcnt vmcnt(0)
	s_barrier
	s_cmp_lt_u32 s24, 2
	s_cbranch_scc0 .Lsg3_next
	ds_read_b128 v[162:165], v184 offset:0
	ds_read_b128 v[166:169], v184 offset:1024
	ds_read_b128 v[170:173], v184 offset:2048
	ds_read_b128 v[174:177], v184 offset:3072
	s_waitcnt lgkmcnt(2)
	v_mfma_f32_32x32x16_bf16 v[2:17], v[34:37], v[162:165], 0
	v_mfma_f32_32x32x16_bf16 v[18:33], v[34:37], v[166:169], 0
	ds_read_b128 v[162:165], v184 offset:4096
	ds_read_b128 v[166:169], v184 offset:5120
	s_waitcnt lgkmcnt(2)
	v_mfma_f32_32x32x16_bf16 v[2:17], v[38:41], v[170:173], v[2:17]
	v_mfma_f32_32x32x16_bf16 v[18:33], v[38:41], v[174:177], v[18:33]
	ds_read_b128 v[170:173], v184 offset:6144
	ds_read_b128 v[174:177], v184 offset:7168
	s_waitcnt lgkmcnt(2)
	v_mfma_f32_32x32x16_bf16 v[2:17], v[42:45], v[162:165], v[2:17]
	v_mfma_f32_32x32x16_bf16 v[18:33], v[42:45], v[166:169], v[18:33]
	ds_read_b128 v[162:165], v184 offset:8192
	ds_read_b128 v[166:169], v184 offset:9216
	s_waitcnt lgkmcnt(2)
	v_mfma_f32_32x32x16_bf16 v[2:17], v[46:49], v[170:173], v[2:17]
	v_mfma_f32_32x32x16_bf16 v[18:33], v[46:49], v[174:177], v[18:33]
	ds_read_b128 v[170:173], v184 offset:10240
	ds_read_b128 v[174:177], v184 offset:11264
	s_waitcnt lgkmcnt(2)
	v_mfma_f32_32x32x16_bf16 v[2:17], v[50:53], v[162:165], v[2:17]
	v_mfma_f32_32x32x16_bf16 v[18:33], v[50:53], v[166:169], v[18:33]
	ds_read_b128 v[162:165], v184 offset:12288
	ds_read_b128 v[166:169], v184 offset:13312
	s_waitcnt lgkmcnt(2)
	v_mfma_f32_32x32x16_bf16 v[2:17], v[54:57], v[170:173], v[2:17]
	v_mfma_f32_32x32x16_bf16 v[18:33], v[54:57], v[174:177], v[18:33]
	ds_read_b128 v[170:173], v184 offset:14336
	ds_read_b128 v[174:177], v184 offset:15360
	s_waitcnt lgkmcnt(2)
	v_mfma_f32_32x32x16_bf16 v[2:17], v[58:61], v[162:165], v[2:17]
	v_mfma_f32_32x32x16_bf16 v[18:33], v[58:61], v[166:169], v[18:33]
	ds_read_b128 v[162:165], v184 offset:16384
	ds_read_b128 v[166:169], v184 offset:17408
	s_waitcnt lgkmcnt(2)
	v_mfma_f32_32x32x16_bf16 v[2:17], v[62:65], v[170:173], v[2:17]
	v_mfma_f32_32x32x16_bf16 v[18:33], v[62:65], v[174:177], v[18:33]
	ds_read_b128 v[170:173], v184 offset:18432
	ds_read_b128 v[174:177], v184 offset:19456
	s_waitcnt lgkmcnt(2)
	v_mfma_f32_32x32x16_bf16 v[2:17], v[66:69], v[162:165], v[2:17]
	v_mfma_f32_32x32x16_bf16 v[18:33], v[66:69], v[166:169], v[18:33]
	ds_read_b128 v[162:165], v184 offset:20480
	ds_read_b128 v[166:169], v184 offset:21504
	s_waitcnt lgkmcnt(2)
	v_mfma_f32_32x32x16_bf16 v[2:17], v[70:73], v[170:173], v[2:17]
	v_mfma_f32_32x32x16_bf16 v[18:33], v[70:73], v[174:177], v[18:33]
	ds_read_b128 v[170:173], v184 offset:22528
	ds_read_b128 v[174:177], v184 offset:23552
	s_waitcnt lgkmcnt(2)
	v_mfma_f32_32x32x16_bf16 v[2:17], v[74:77], v[162:165], v[2:17]
	v_mfma_f32_32x32x16_bf16 v[18:33], v[74:77], v[166:169], v[18:33]
	ds_read_b128 v[162:165], v184 offset:24576
	ds_read_b128 v[166:169], v184 offset:25600
	s_waitcnt lgkmcnt(2)
	v_mfma_f32_32x32x16_bf16 v[2:17], v[78:81], v[170:173], v[2:17]
	v_mfma_f32_32x32x16_bf16 v[18:33], v[78:81], v[174:177], v[18:33]
	ds_read_b128 v[170:173], v184 offset:26624
	ds_read_b128 v[174:177], v184 offset:27648
	s_waitcnt lgkmcnt(2)
	v_mfma_f32_32x32x16_bf16 v[2:17], v[82:85], v[162:165], v[2:17]
	v_mfma_f32_32x32x16_bf16 v[18:33], v[82:85], v[166:169], v[18:33]
	ds_read_b128 v[162:165], v184 offset:28672
	ds_read_b128 v[166:169], v184 offset:29696
	s_waitcnt lgkmcnt(2)
	v_mfma_f32_32x32x16_bf16 v[2:17], v[86:89], v[170:173], v[2:17]
	v_mfma_f32_32x32x16_bf16 v[18:33], v[86:89], v[174:177], v[18:33]
	ds_read_b128 v[170:173], v184 offset:30720
	ds_read_b128 v[174:177], v184 offset:31744
	s_waitcnt lgkmcnt(2)
	v_mfma_f32_32x32x16_bf16 v[2:17], v[90:93], v[162:165], v[2:17]
	v_mfma_f32_32x32x16_bf16 v[18:33], v[90:93], v[166:169], v[18:33]
	ds_read_b128 v[162:165], v184 offset:32768
	ds_read_b128 v[166:169], v184 offset:33792
	s_waitcnt lgkmcnt(2)
	v_mfma_f32_32x32x16_bf16 v[2:17], v[94:97], v[170:173], v[2:17]
	v_mfma_f32_32x32x16_bf16 v[18:33], v[94:97], v[174:177], v[18:33]
	ds_read_b128 v[170:173], v184 offset:34816
	ds_read_b128 v[174:177], v184 offset:35840
	s_waitcnt lgkmcnt(2)
	v_mfma_f32_32x32x16_bf16 v[2:17], v[98:101], v[162:165], v[2:17]
	v_mfma_f32_32x32x16_bf16 v[18:33], v[98:101], v[166:169], v[18:33]
	ds_read_b128 v[162:165], v184 offset:36864
	ds_read_b128 v[166:169], v184 offset:37888
	s_waitcnt lgkmcnt(2)
	v_mfma_f32_32x32x16_bf16 v[2:17], v[102:105], v[170:173], v[2:17]
	v_mfma_f32_32x32x16_bf16 v[18:33], v[102:105], v[174:177], v[18:33]
	ds_read_b128 v[170:173], v184 offset:38912
	ds_read_b128 v[174:177], v184 offset:39936
	s_waitcnt lgkmcnt(2)
	v_mfma_f32_32x32x16_bf16 v[2:17], v[106:109], v[162:165], v[2:17]
	v_mfma_f32_32x32x16_bf16 v[18:33], v[106:109], v[166:169], v[18:33]
	ds_read_b128 v[162:165], v184 offset:40960
	ds_read_b128 v[166:169], v184 offset:41984
	s_waitcnt lgkmcnt(2)
	v_mfma_f32_32x32x16_bf16 v[2:17], v[110:113], v[170:173], v[2:17]
	v_mfma_f32_32x32x16_bf16 v[18:33], v[110:113], v[174:177], v[18:33]
	ds_read_b128 v[170:173], v184 offset:43008
	ds_read_b128 v[174:177], v184 offset:44032
	s_waitcnt lgkmcnt(2)
	v_mfma_f32_32x32x16_bf16 v[2:17], v[114:117], v[162:165], v[2:17]
	v_mfma_f32_32x32x16_bf16 v[18:33], v[114:117], v[166:169], v[18:33]
	ds_read_b128 v[162:165], v184 offset:45056
	ds_read_b128 v[166:169], v184 offset:46080
	s_waitcnt lgkmcnt(2)
	v_mfma_f32_32x32x16_bf16 v[2:17], v[118:121], v[170:173], v[2:17]
	v_mfma_f32_32x32x16_bf16 v[18:33], v[118:121], v[174:177], v[18:33]
	ds_read_b128 v[170:173], v184 offset:47104
	ds_read_b128 v[174:177], v184 offset:48128
	s_waitcnt lgkmcnt(2)
	v_mfma_f32_32x32x16_bf16 v[2:17], v[122:125], v[162:165], v[2:17]
	v_mfma_f32_32x32x16_bf16 v[18:33], v[122:125], v[166:169], v[18:33]
	ds_read_b128 v[162:165], v184 offset:49152
	ds_read_b128 v[166:169], v184 offset:50176
	s_waitcnt lgkmcnt(2)
	v_mfma_f32_32x32x16_bf16 v[2:17], v[126:129], v[170:173], v[2:17]
	v_mfma_f32_32x32x16_bf16 v[18:33], v[126:129], v[174:177], v[18:33]
	ds_read_b128 v[170:173], v184 offset:51200
	ds_read_b128 v[174:177], v184 offset:52224
	s_waitcnt lgkmcnt(2)
	v_mfma_f32_32x32x16_bf16 v[2:17], v[130:133], v[162:165], v[2:17]
	v_mfma_f32_32x32x16_bf16 v[18:33], v[130:133], v[166:169], v[18:33]
	ds_read_b128 v[162:165], v184 offset:53248
	ds_read_b128 v[166:169], v184 offset:54272
	s_waitcnt lgkmcnt(2)
	v_mfma_f32_32x32x16_bf16 v[2:17], v[134:137], v[170:173], v[2:17]
	v_mfma_f32_32x32x16_bf16 v[18:33], v[134:137], v[174:177], v[18:33]
	ds_read_b128 v[170:173], v184 offset:55296
	ds_read_b128 v[174:177], v184 offset:56320
	s_waitcnt lgkmcnt(2)
	v_mfma_f32_32x32x16_bf16 v[2:17], v[138:141], v[162:165], v[2:17]
	v_mfma_f32_32x32x16_bf16 v[18:33], v[138:141], v[166:169], v[18:33]
	ds_read_b128 v[162:165], v184 offset:57344
	ds_read_b128 v[166:169], v184 offset:58368
	s_waitcnt lgkmcnt(2)
	v_mfma_f32_32x32x16_bf16 v[2:17], v[142:145], v[170:173], v[2:17]
	v_mfma_f32_32x32x16_bf16 v[18:33], v[142:145], v[174:177], v[18:33]
	ds_read_b128 v[170:173], v184 offset:59392
	ds_read_b128 v[174:177], v184 offset:60416
	s_waitcnt lgkmcnt(2)
	v_mfma_f32_32x32x16_bf16 v[2:17], v[146:149], v[162:165], v[2:17]
	v_mfma_f32_32x32x16_bf16 v[18:33], v[146:149], v[166:169], v[18:33]
	ds_read_b128 v[162:165], v184 offset:61440
	ds_read_b128 v[166:169], v184 offset:62464
	s_waitcnt lgkmcnt(2)
	v_mfma_f32_32x32x16_bf16 v[2:17], v[150:153], v[170:173], v[2:17]
	v_mfma_f32_32x32x16_bf16 v[18:33], v[150:153], v[174:177], v[18:33]
	ds_read_b128 v[170:173], v184 offset:63488
	ds_read_b128 v[174:177], v184 offset:64512
	s_waitcnt lgkmcnt(2)
	v_mfma_f32_32x32x16_bf16 v[2:17], v[154:157], v[162:165], v[2:17]
	v_mfma_f32_32x32x16_bf16 v[18:33], v[154:157], v[166:169], v[18:33]
	s_waitcnt lgkmcnt(0)
	v_mfma_f32_32x32x16_bf16 v[2:17], v[158:161], v[170:173], v[2:17]
	v_mfma_f32_32x32x16_bf16 v[18:33], v[158:161], v[174:177], v[18:33]
	s_nop 15
	s_nop 3
	global_store_dword v181, v2, s[22:23]
	global_store_dword v181, v18, s[22:23] offset:128
	v_add_u32_e32 v188, 0x1000, v181
	global_store_dword v188, v3, s[22:23]
	global_store_dword v188, v19, s[22:23] offset:128
	v_add_u32_e32 v187, 0x2000, v181
	global_store_dword v187, v4, s[22:23]
	global_store_dword v187, v20, s[22:23] offset:128
	v_add_u32_e32 v188, 0x3000, v181
	global_store_dword v188, v5, s[22:23]
	global_store_dword v188, v21, s[22:23] offset:128
	v_add_u32_e32 v187, 0x8000, v181
	global_store_dword v187, v6, s[22:23]
	global_store_dword v187, v22, s[22:23] offset:128
	v_add_u32_e32 v188, 0x9000, v181
	global_store_dword v188, v7, s[22:23]
	global_store_dword v188, v23, s[22:23] offset:128
	v_add_u32_e32 v187, 0xa000, v181
	global_store_dword v187, v8, s[22:23]
	global_store_dword v187, v24, s[22:23] offset:128
	v_add_u32_e32 v188, 0xb000, v181
	global_store_dword v188, v9, s[22:23]
	global_store_dword v188, v25, s[22:23] offset:128
	v_add_u32_e32 v187, 0x10000, v181
	global_store_dword v187, v10, s[22:23]
	global_store_dword v187, v26, s[22:23] offset:128
	v_add_u32_e32 v188, 0x11000, v181
	global_store_dword v188, v11, s[22:23]
	global_store_dword v188, v27, s[22:23] offset:128
	v_add_u32_e32 v187, 0x12000, v181
	global_store_dword v187, v12, s[22:23]
	global_store_dword v187, v28, s[22:23] offset:128
	v_add_u32_e32 v188, 0x13000, v181
	global_store_dword v188, v13, s[22:23]
	global_store_dword v188, v29, s[22:23] offset:128
	v_add_u32_e32 v187, 0x18000, v181
	global_store_dword v187, v14, s[22:23]
	global_store_dword v187, v30, s[22:23] offset:128
	v_add_u32_e32 v188, 0x19000, v181
	global_store_dword v188, v15, s[22:23]
	global_store_dword v188, v31, s[22:23] offset:128
	v_add_u32_e32 v187, 0x1a000, v181
	global_store_dword v187, v16, s[22:23]
	global_store_dword v187, v32, s[22:23] offset:128
	v_add_u32_e32 v188, 0x1b000, v181
	global_store_dword v188, v17, s[22:23]
	global_store_dword v188, v33, s[22:23] offset:128
.Lsg3_next:
	s_add_u32 s25, s25, s3
	s_cmpk_gt_u32 s25, 0xff
	s_cbranch_scc1 .Lsg3_done
	s_waitcnt lgkmcnt(0)
	s_barrier
	s_branch .Lsg3_wg
.Lsg3_done:
	s_waitcnt lgkmcnt(0)
.LBB3_3:
	s_barrier
	s_cmpk_gt_i32 s2, 0xff
	v_readfirstlane_b32 s14, v0
	s_cbranch_scc1 .LBB3_27
	s_ashr_i32 s30, s2, 31
	s_lshr_b32 s4, s30, 29
	s_add_i32 s10, s2, s4
	s_and_b32 s4, s10, -8
	s_sub_i32 s8, s2, s4
	s_cmp_gt_i32 s8, -1
	s_cbranch_scc0 .LBB3_6
	s_lshl_b32 s9, s8, 5
	s_ashr_i32 s4, s10, 3
	s_cbranch_execz .LBB3_7
	s_branch .LBB3_8

_Z10fwd_kernelILi6ELi7EEv4Args:
	v_mov_b32_e32 v1, v0
	s_load_dword s3, s[0:1], 0xe8
	s_load_dwordx2 s[0:1], s[0:1], 0xd8
	v_readfirstlane_b32 s4, v1
	s_ashr_i32 s4, s4, 6
	s_waitcnt lgkmcnt(0)
	s_add_u32 s6, s0, 0x1100000
	s_addc_u32 s7, s1, 0
	s_add_u32 s20, s0, 0xf400000
	s_addc_u32 s21, s1, 0
	s_add_u32 s22, s0, 0x100000
	s_addc_u32 s23, s1, 0
	v_readfirstlane_b32 s24, v0
	s_lshr_b32 s24, s24, 6
	v_and_b32_e32 v185, 31, v0
	v_bfe_u32 v186, v0, 5, 1
	v_and_b32_e32 v187, 63, v0
	v_lshlrev_b32_e32 v182, 13, v185
	v_lshl_add_u32 v182, v186, 4, v182
	v_lshlrev_b32_e32 v183, 2, v185
	v_lshl_add_u32 v183, v186, 14, v183
	v_lshlrev_b32_e32 v184, 4, v187
	s_mov_b32 s25, s2
	s_cmpk_gt_u32 s25, 0xff
	s_cbranch_scc1 .Lsg6_done
.Lsg6_wg:
	s_and_b32 s26, s25, 7
	s_lshr_b32 s27, s25, 3
	s_mov_b32 s29, s26
	s_lshr_b32 s28, s27, 1
	s_and_b32 s30, s27, 1
	s_lshl_b32 s30, s30, 3
	s_add_u32 s30, s30, s24
	s_lshl_b32 s31, s29, 10
	s_lshl_b32 s33, s28, 19
	s_add_u32 s33, s33, s31
	s_lshl_b32 s34, s24, 7
	s_add_u32 s33, s33, s34
	s_add_u32 s36, s6, s33
	s_addc_u32 s37, s7, 0
	v_mov_b32_e32 v179, v182
	v_add_u32_e32 v180, 0x40000, v182
	s_lshl_b32 s33, s30, 18
	s_add_u32 s33, s33, s31
	v_add_u32_e32 v178, s33, v182
	s_lshl_b32 s33, s29, 21
	s_lshl_b32 s34, s30, 17
	s_add_u32 s33, s33, s34
	s_lshl_b32 s34, s28, 8
	s_add_u32 s33, s33, s34
	v_add_u32_e32 v181, s33, v183
	s_lshl_b32 s35, s24, 13
	s_cmp_lt_u32 s24, 8
	s_cbranch_scc0 .Lsg6_wonly
	s_add_i32 m0, s35, 0x0
	global_load_dwordx4 v[34:37], v178, s[20:21] offset:0
	global_load_dwordx4 v[38:41], v178, s[20:21] offset:32
	global_load_dwordx4 v[42:45], v178, s[20:21] offset:64
	global_load_dwordx4 v[46:49], v178, s[20:21] offset:96
	global_load_lds_dwordx4 v179, s[36:37]
	s_add_i32 m0, s35, 0x400
	global_load_dwordx4 v[50:53], v178, s[20:21] offset:128
	global_load_dwordx4 v[54:57], v178, s[20:21] offset:160
	global_load_dwordx4 v[58:61], v178, s[20:21] offset:192
	global_load_dwordx4 v[62:65], v178, s[20:21] offset:224
	global_load_lds_dwordx4 v180, s[36:37]
	s_add_u32 s36, s36, 32
	s_addc_u32 s37, s37, 0
	s_add_i32 m0, s35, 0x800
	global_load_dwordx4 v[66:69], v178, s[20:21] offset:256
	global_load_dwordx4 v[70:73], v178, s[20:21] offset:288
	global_load_dwordx4 v[74:77], v178, s[20:21] offset:320
	global_load_dwordx4 v[78:81], v178, s[20:21] offset:352
	global_load_lds_dwordx4 v179, s[36:37]
	s_add_i32 m0, s35, 0xc00
	global_load_dwordx4 v[82:85], v178, s[20:21] offset:384
	global_load_dwordx4 v[86:89], v178, s[20:21] offset:416
	global_load_dwordx4 v[90:93], v178, s[20:21] offset:448
	global_load_dwordx4 v[94:97], v178, s[20:21] offset:480
	global_load_lds_dwordx4 v180, s[36:37]
	s_add_u32 s36, s36, 32
	s_addc_u32 s37, s37, 0
	s_add_i32 m0, s35, 0x1000
	global_load_dwordx4 v[98:101], v178, s[20:21] offset:512
	global_load_dwordx4 v[102:105], v178, s[20:21] offset:544
	global_load_dwordx4 v[106:109], v178, s[20:21] offset:576
	global_load_dwordx4 v[110:113], v178, s[20:21] offset:608
	global_load_lds_dwordx4 v179, s[36:37]
	s_add_i32 m0, s35, 0x1400
	global_load_dwordx4 v[114:117], v178, s[20:21] offset:640
	global_load_dwordx4 v[118:121], v178, s[20:21] offset:672
	global_load_dwordx4 v[122:125], v178, s[20:21] offset:704
	global_load_dwordx4 v[126:129], v178, s[20:21] offset:736
	global_load_lds_dwordx4 v180, s[36:37]
	s_add_u32 s36, s36, 32
	s_addc_u32 s37, s37, 0
	s_add_i32 m0, s35, 0x1800
	global_load_dwordx4 v[130:133], v178, s[20:21] offset:768
	global_load_dwordx4 v[134:137], v178, s[20:21] offset:800
	global_load_dwordx4 v[138:141], v178, s[20:21] offset:832
	global_load_dwordx4 v[142:145], v178, s[20:21] offset:864
	global_load_lds_dwordx4 v179, s[36:37]
	s_add_i32 m0, s35, 0x1c00
	global_load_dwordx4 v[146:149], v178, s[20:21] offset:896
	global_load_dwordx4 v[150:153], v178, s[20:21] offset:928
	global_load_dwordx4 v[154:157], v178, s[20:21] offset:960
	global_load_dwordx4 v[158:161], v178, s[20:21] offset:992
	global_load_lds_dwordx4 v180, s[36:37]
.Lsg6_wonly:
	s_waitcnt vmcnt(0)
	s_barrier
	s_cmp_lt_u32 s24, 8
	s_cbranch_scc0 .Lsg6_next
	ds_read_b128 v[162:165], v184 offset:0
	ds_read_b128 v[166:169], v184 offset:1024
	ds_read_b128 v[170:173], v184 offset:2048
	ds_read_b128 v[174:177], v184 offset:3072
	s_waitcnt lgkmcnt(2)
	v_mfma_f32_32x32x16_bf16 v[2:17], v[34:37], v[162:165], 0
	v_mfma_f32_32x32x16_bf16 v[18:33], v[34:37], v[166:169], 0
	ds_read_b128 v[162:165], v184 offset:4096
	ds_read_b128 v[166:169], v184 offset:5120
	s_waitcnt lgkmcnt(2)
	v_mfma_f32_32x32x16_bf16 v[2:17], v[38:41], v[170:173], v[2:17]
	v_mfma_f32_32x32x16_bf16 v[18:33], v[38:41], v[174:177], v[18:33]
	ds_read_b128 v[170:173], v184 offset:6144
	ds_read_b128 v[174:177], v184 offset:7168
	s_waitcnt lgkmcnt(2)
	v_mfma_f32_32x32x16_bf16 v[2:17], v[42:45], v[162:165], v[2:17]
	v_mfma_f32_32x32x16_bf16 v[18:33], v[42:45], v[166:169], v[18:33]
	ds_read_b128 v[162:165], v184 offset:8192
	ds_read_b128 v[166:169], v184 offset:9216
	s_waitcnt lgkmcnt(2)
	v_mfma_f32_32x32x16_bf16 v[2:17], v[46:49], v[170:173], v[2:17]
	v_mfma_f32_32x32x16_bf16 v[18:33], v[46:49], v[174:177], v[18:33]
	ds_read_b128 v[170:173], v184 offset:10240
	ds_read_b128 v[174:177], v184 offset:11264
	s_waitcnt lgkmcnt(2)
	v_mfma_f32_32x32x16_bf16 v[2:17], v[50:53], v[162:165], v[2:17]
	v_mfma_f32_32x32x16_bf16 v[18:33], v[50:53], v[166:169], v[18:33]
	ds_read_b128 v[162:165], v184 offset:12288
	ds_read_b128 v[166:169], v184 offset:13312
	s_waitcnt lgkmcnt(2)
	v_mfma_f32_32x32x16_bf16 v[2:17], v[54:57], v[170:173], v[2:17]
	v_mfma_f32_32x32x16_bf16 v[18:33], v[54:57], v[174:177], v[18:33]
	ds_read_b128 v[170:173], v184 offset:14336
	ds_read_b128 v[174:177], v184 offset:15360
	s_waitcnt lgkmcnt(2)
	v_mfma_f32_32x32x16_bf16 v[2:17], v[58:61], v[162:165], v[2:17]
	v_mfma_f32_32x32x16_bf16 v[18:33], v[58:61], v[166:169], v[18:33]
	ds_read_b128 v[162:165], v184 offset:16384
	ds_read_b128 v[166:169], v184 offset:17408
	s_waitcnt lgkmcnt(2)
	v_mfma_f32_32x32x16_bf16 v[2:17], v[62:65], v[170:173], v[2:17]
	v_mfma_f32_32x32x16_bf16 v[18:33], v[62:65], v[174:177], v[18:33]
	ds_read_b128 v[170:173], v184 offset:18432
	ds_read_b128 v[174:177], v184 offset:19456
	s_waitcnt lgkmcnt(2)
	v_mfma_f32_32x32x16_bf16 v[2:17], v[66:69], v[162:165], v[2:17]
	v_mfma_f32_32x32x16_bf16 v[18:33], v[66:69], v[166:169], v[18:33]
	ds_read_b128 v[162:165], v184 offset:20480
	ds_read_b128 v[166:169], v184 offset:21504
	s_waitcnt lgkmcnt(2)
	v_mfma_f32_32x32x16_bf16 v[2:17], v[70:73], v[170:173], v[2:17]
	v_mfma_f32_32x32x16_bf16 v[18:33], v[70:73], v[174:177], v[18:33]
	ds_read_b128 v[170:173], v184 offset:22528
	ds_read_b128 v[174:177], v184 offset:23552
	s_waitcnt lgkmcnt(2)
	v_mfma_f32_32x32x16_bf16 v[2:17], v[74:77], v[162:165], v[2:17]
	v_mfma_f32_32x32x16_bf16 v[18:33], v[74:77], v[166:169], v[18:33]
	ds_read_b128 v[162:165], v184 offset:24576
	ds_read_b128 v[166:169], v184 offset:25600
	s_waitcnt lgkmcnt(2)
	v_mfma_f32_32x32x16_bf16 v[2:17], v[78:81], v[170:173], v[2:17]
	v_mfma_f32_32x32x16_bf16 v[18:33], v[78:81], v[174:177], v[18:33]
	ds_read_b128 v[170:173], v184 offset:26624
	ds_read_b128 v[174:177], v184 offset:27648
	s_waitcnt lgkmcnt(2)
	v_mfma_f32_32x32x16_bf16 v[2:17], v[82:85], v[162:165], v[2:17]
	v_mfma_f32_32x32x16_bf16 v[18:33], v[82:85], v[166:169], v[18:33]
	ds_read_b128 v[162:165], v184 offset:28672
	ds_read_b128 v[166:169], v184 offset:29696
	s_waitcnt lgkmcnt(2)
	v_mfma_f32_32x32x16_bf16 v[2:17], v[86:89], v[170:173], v[2:17]
	v_mfma_f32_32x32x16_bf16 v[18:33], v[86:89], v[174:177], v[18:33]
	ds_read_b128 v[170:173], v184 offset:30720
	ds_read_b128 v[174:177], v184 offset:31744
	s_waitcnt lgkmcnt(2)
	v_mfma_f32_32x32x16_bf16 v[2:17], v[90:93], v[162:165], v[2:17]
	v_mfma_f32_32x32x16_bf16 v[18:33], v[90:93], v[166:169], v[18:33]
	ds_read_b128 v[162:165], v184 offset:32768
	ds_read_b128 v[166:169], v184 offset:33792
	s_waitcnt lgkmcnt(2)
	v_mfma_f32_32x32x16_bf16 v[2:17], v[94:97], v[170:173], v[2:17]
	v_mfma_f32_32x32x16_bf16 v[18:33], v[94:97], v[174:177], v[18:33]
	ds_read_b128 v[170:173], v184 offset:34816
	ds_read_b128 v[174:177], v184 offset:35840
	s_waitcnt lgkmcnt(2)
	v_mfma_f32_32x32x16_bf16 v[2:17], v[98:101], v[162:165], v[2:17]
	v_mfma_f32_32x32x16_bf16 v[18:33], v[98:101], v[166:169], v[18:33]
	ds_read_b128 v[162:165], v184 offset:36864
	ds_read_b128 v[166:169], v184 offset:37888
	s_waitcnt lgkmcnt(2)
	v_mfma_f32_32x32x16_bf16 v[2:17], v[102:105], v[170:173], v[2:17]
	v_mfma_f32_32x32x16_bf16 v[18:33], v[102:105], v[174:177], v[18:33]
	ds_read_b128 v[170:173], v184 offset:38912
	ds_read_b128 v[174:177], v184 offset:39936
	s_waitcnt lgkmcnt(2)
	v_mfma_f32_32x32x16_bf16 v[2:17], v[106:109], v[162:165], v[2:17]
	v_mfma_f32_32x32x16_bf16 v[18:33], v[106:109], v[166:169], v[18:33]
	ds_read_b128 v[162:165], v184 offset:40960
	ds_read_b128 v[166:169], v184 offset:41984
	s_waitcnt lgkmcnt(2)
	v_mfma_f32_32x32x16_bf16 v[2:17], v[110:113], v[170:173], v[2:17]
	v_mfma_f32_32x32x16_bf16 v[18:33], v[110:113], v[174:177], v[18:33]
	ds_read_b128 v[170:173], v184 offset:43008
	ds_read_b128 v[174:177], v184 offset:44032
	s_waitcnt lgkmcnt(2)
	v_mfma_f32_32x32x16_bf16 v[2:17], v[114:117], v[162:165], v[2:17]
	v_mfma_f32_32x32x16_bf16 v[18:33], v[114:117], v[166:169], v[18:33]
	ds_read_b128 v[162:165], v184 offset:45056
	ds_read_b128 v[166:169], v184 offset:46080
	s_waitcnt lgkmcnt(2)
	v_mfma_f32_32x32x16_bf16 v[2:17], v[118:121], v[170:173], v[2:17]
	v_mfma_f32_32x32x16_bf16 v[18:33], v[118:121], v[174:177], v[18:33]
	ds_read_b128 v[170:173], v184 offset:47104
	ds_read_b128 v[174:177], v184 offset:48128
	s_waitcnt lgkmcnt(2)
	v_mfma_f32_32x32x16_bf16 v[2:17], v[122:125], v[162:165], v[2:17]
	v_mfma_f32_32x32x16_bf16 v[18:33], v[122:125], v[166:169], v[18:33]
	ds_read_b128 v[162:165], v184 offset:49152
	ds_read_b128 v[166:169], v184 offset:50176
	s_waitcnt lgkmcnt(2)
	v_mfma_f32_32x32x16_bf16 v[2:17], v[126:129], v[170:173], v[2:17]
	v_mfma_f32_32x32x16_bf16 v[18:33], v[126:129], v[174:177], v[18:33]
	ds_read_b128 v[170:173], v184 offset:51200
	ds_read_b128 v[174:177], v184 offset:52224
	s_waitcnt lgkmcnt(2)
	v_mfma_f32_32x32x16_bf16 v[2:17], v[130:133], v[162:165], v[2:17]
	v_mfma_f32_32x32x16_bf16 v[18:33], v[130:133], v[166:169], v[18:33]
	ds_read_b128 v[162:165], v184 offset:53248
	ds_read_b128 v[166:169], v184 offset:54272
	s_waitcnt lgkmcnt(2)
	v_mfma_f32_32x32x16_bf16 v[2:17], v[134:137], v[170:173], v[2:17]
	v_mfma_f32_32x32x16_bf16 v[18:33], v[134:137], v[174:177], v[18:33]
	ds_read_b128 v[170:173], v184 offset:55296
	ds_read_b128 v[174:177], v184 offset:56320
	s_waitcnt lgkmcnt(2)
	v_mfma_f32_32x32x16_bf16 v[2:17], v[138:141], v[162:165], v[2:17]
	v_mfma_f32_32x32x16_bf16 v[18:33], v[138:141], v[166:169], v[18:33]
	ds_read_b128 v[162:165], v184 offset:57344
	ds_read_b128 v[166:169], v184 offset:58368
	s_waitcnt lgkmcnt(2)
	v_mfma_f32_32x32x16_bf16 v[2:17], v[142:145], v[170:173], v[2:17]
	v_mfma_f32_32x32x16_bf16 v[18:33], v[142:145], v[174:177], v[18:33]
	ds_read_b128 v[170:173], v184 offset:59392
	ds_read_b128 v[174:177], v184 offset:60416
	s_waitcnt lgkmcnt(2)
	v_mfma_f32_32x32x16_bf16 v[2:17], v[146:149], v[162:165], v[2:17]
	v_mfma_f32_32x32x16_bf16 v[18:33], v[146:149], v[166:169], v[18:33]
	ds_read_b128 v[162:165], v184 offset:61440
	ds_read_b128 v[166:169], v184 offset:62464
	s_waitcnt lgkmcnt(2)
	v_mfma_f32_32x32x16_bf16 v[2:17], v[150:153], v[170:173], v[2:17]
	v_mfma_f32_32x32x16_bf16 v[18:33], v[150:153], v[174:177], v[18:33]
	ds_read_b128 v[170:173], v184 offset:63488
	ds_read_b128 v[174:177], v184 offset:64512
	s_waitcnt lgkmcnt(2)
	v_mfma_f32_32x32x16_bf16 v[2:17], v[154:157], v[162:165], v[2:17]
	v_mfma_f32_32x32x16_bf16 v[18:33], v[154:157], v[166:169], v[18:33]
	s_waitcnt lgkmcnt(0)
	v_mfma_f32_32x32x16_bf16 v[2:17], v[158:161], v[170:173], v[2:17]
	v_mfma_f32_32x32x16_bf16 v[18:33], v[158:161], v[174:177], v[18:33]
	s_nop 15
	s_nop 3
	global_store_dword v181, v2, s[22:23]
	global_store_dword v181, v18, s[22:23] offset:128
	v_add_u32_e32 v188, 0x1000, v181
	global_store_dword v188, v3, s[22:23]
	global_store_dword v188, v19, s[22:23] offset:128
	v_add_u32_e32 v187, 0x2000, v181
	global_store_dword v187, v4, s[22:23]
	global_store_dword v187, v20, s[22:23] offset:128
	v_add_u32_e32 v188, 0x3000, v181
	global_store_dword v188, v5, s[22:23]
	global_store_dword v188, v21, s[22:23] offset:128
	v_add_u32_e32 v187, 0x8000, v181
	global_store_dword v187, v6, s[22:23]
	global_store_dword v187, v22, s[22:23] offset:128
	v_add_u32_e32 v188, 0x9000, v181
	global_store_dword v188, v7, s[22:23]
	global_store_dword v188, v23, s[22:23] offset:128
	v_add_u32_e32 v187, 0xa000, v181
	global_store_dword v187, v8, s[22:23]
	global_store_dword v187, v24, s[22:23] offset:128
	v_add_u32_e32 v188, 0xb000, v181
	global_store_dword v188, v9, s[22:23]
	global_store_dword v188, v25, s[22:23] offset:128
	v_add_u32_e32 v187, 0x10000, v181
	global_store_dword v187, v10, s[22:23]
	global_store_dword v187, v26, s[22:23] offset:128
	v_add_u32_e32 v188, 0x11000, v181
	global_store_dword v188, v11, s[22:23]
	global_store_dword v188, v27, s[22:23] offset:128
	v_add_u32_e32 v187, 0x12000, v181
	global_store_dword v187, v12, s[22:23]
	global_store_dword v187, v28, s[22:23] offset:128
	v_add_u32_e32 v188, 0x13000, v181
	global_store_dword v188, v13, s[22:23]
	global_store_dword v188, v29, s[22:23] offset:128
	v_add_u32_e32 v187, 0x18000, v181
	global_store_dword v187, v14, s[22:23]
	global_store_dword v187, v30, s[22:23] offset:128
	v_add_u32_e32 v188, 0x19000, v181
	global_store_dword v188, v15, s[22:23]
	global_store_dword v188, v31, s[22:23] offset:128
	v_add_u32_e32 v187, 0x1a000, v181
	global_store_dword v187, v16, s[22:23]
	global_store_dword v187, v32, s[22:23] offset:128
	v_add_u32_e32 v188, 0x1b000, v181
	global_store_dword v188, v17, s[22:23]
	global_store_dword v188, v33, s[22:23] offset:128

.Lsg6_done:
	s_waitcnt lgkmcnt(0)
.LBB6_3:
	s_barrier
	s_cmpk_gt_i32 s2, 0xff
	v_readfirstlane_b32 s14, v0
	s_cbranch_scc1 .LBB6_27
	s_ashr_i32 s30, s2, 31
	s_lshr_b32 s4, s30, 29
	s_add_i32 s10, s2, s4
	s_and_b32 s4, s10, -8
	s_sub_i32 s8, s2, s4
	s_cmp_gt_i32 s8, -1
	s_cbranch_scc0 .LBB6_6
	s_lshl_b32 s9, s8, 5
	s_ashr_i32 s4, s10, 3
	s_cbranch_execz .LBB6_7
	s_branch .LBB6_8

_Z10fwd_kernelILi10ELi11EEv4Args:
	v_mov_b32_e32 v1, v0
	s_load_dword s3, s[0:1], 0xe8
	s_load_dwordx2 s[0:1], s[0:1], 0xd8
	v_readfirstlane_b32 s4, v1
	s_ashr_i32 s6, s4, 6
	s_waitcnt lgkmcnt(0)
	s_add_u32 s4, s0, 0x1f00000
	s_addc_u32 s5, s1, 0
	s_add_u32 s20, s0, 0xf700000
	s_addc_u32 s21, s1, 0
	s_add_u32 s22, s0, 0x7400000
	s_addc_u32 s23, s1, 0
	v_readfirstlane_b32 s24, v0
	s_lshr_b32 s24, s24, 6
	v_and_b32_e32 v185, 31, v0
	v_bfe_u32 v186, v0, 5, 1
	v_and_b32_e32 v187, 63, v0
	v_lshlrev_b32_e32 v182, 11, v185
	v_lshl_add_u32 v182, v186, 4, v182
	v_lshlrev_b32_e32 v183, 2, v185
	v_lshl_add_u32 v183, v186, 14, v183
	v_lshlrev_b32_e32 v184, 4, v187
	s_mov_b32 s25, s2
	s_cmpk_gt_u32 s25, 0xff
	s_cbranch_scc1 .Lsg10_done
.Lsg10_wg:
	s_and_b32 s26, s25, 7
	s_lshr_b32 s27, s25, 3
	s_lshl_b32 s28, s26, 1
	s_lshr_b32 s29, s27, 4
	s_add_u32 s28, s28, s29
	s_bfe_u32 s29, s27, 0x10003
	s_and_b32 s30, s27, 7
	s_lshl_b32 s31, s24, 3
	s_add_u32 s30, s30, s31
	s_lshl_b32 s31, s29, 10
	s_lshl_b32 s33, s28, 17
	s_add_u32 s33, s33, s31
	s_lshl_b32 s34, s24, 7
	s_add_u32 s33, s33, s34
	s_add_u32 s36, s4, s33
	s_addc_u32 s37, s5, 0
	v_mov_b32_e32 v179, v182
	v_add_u32_e32 v180, 0x10000, v182
	s_lshl_b32 s33, s30, 16
	s_add_u32 s33, s33, s31
	v_add_u32_e32 v178, s33, v182
	s_lshl_b32 s33, s29, 21
	s_lshl_b32 s34, s30, 17
	s_add_u32 s33, s33, s34
	s_lshl_b32 s34, s28, 8
	s_add_u32 s33, s33, s34
	v_add_u32_e32 v181, s33, v183
	s_lshl_b32 s35, s24, 13
	s_cmp_lt_u32 s24, 2
	s_cbranch_scc0 .Lsg10_wonly
	s_add_i32 m0, s35, 0x0
	global_load_dwordx4 v[34:37], v178, s[20:21] offset:0
	global_load_dwordx4 v[38:41], v178, s[20:21] offset:32
	global_load_dwordx4 v[42:45], v178, s[20:21] offset:64
	global_load_dwordx4 v[46:49], v178, s[20:21] offset:96
	global_load_lds_dwordx4 v179, s[36:37]
	s_add_i32 m0, s35, 0x400
	global_load_dwordx4 v[50:53], v178, s[20:21] offset:128
	global_load_dwordx4 v[54:57], v178, s[20:21] offset:160
	global_load_dwordx4 v[58:61], v178, s[20:21] offset:192
	global_load_dwordx4 v[62:65], v178, s[20:21] offset:224
	global_load_lds_dwordx4 v180, s[36:37]
	s_add_u32 s36, s36, 32
	s_addc_u32 s37, s37, 0
	s_add_i32 m0, s35, 0x800
	global_load_dwordx4 v[66:69], v178, s[20:21] offset:256
	global_load_dwordx4 v[70:73], v178, s[20:21] offset:288
	global_load_dwordx4 v[74:77], v178, s[20:21] offset:320
	global_load_dwordx4 v[78:81], v178, s[20:21] offset:352
	global_load_lds_dwordx4 v179, s[36:37]
	s_add_i32 m0, s35, 0xc00
	global_load_dwordx4 v[82:85], v178, s[20:21] offset:384
	global_load_dwordx4 v[86:89], v178, s[20:21] offset:416
	global_load_dwordx4 v[90:93], v178, s[20:21] offset:448
	global_load_dwordx4 v[94:97], v178, s[20:21] offset:480
	global_load_lds_dwordx4 v180, s[36:37]
	s_add_u32 s36, s36, 32
	s_addc_u32 s37, s37, 0
	s_add_i32 m0, s35, 0x1000
	global_load_dwordx4 v[98:101], v178, s[20:21] offset:512
	global_load_dwordx4 v[102:105], v178, s[20:21] offset:544
	global_load_dwordx4 v[106:109], v178, s[20:21] offset:576
	global_load_dwordx4 v[110:113], v178, s[20:21] offset:608
	global_load_lds_dwordx4 v179, s[36:37]
	s_add_i32 m0, s35, 0x1400
	global_load_dwordx4 v[114:117], v178, s[20:21] offset:640
	global_load_dwordx4 v[118:121], v178, s[20:21] offset:672
	global_load_dwordx4 v[122:125], v178, s[20:21] offset:704
	global_load_dwordx4 v[126:129], v178, s[20:21] offset:736
	global_load_lds_dwordx4 v180, s[36:37]
	s_add_u32 s36, s36, 32
	s_addc_u32 s37, s37, 0
	s_add_i32 m0, s35, 0x1800
	global_load_dwordx4 v[130:133], v178, s[20:21] offset:768
	global_load_dwordx4 v[134:137], v178, s[20:21] offset:800
	global_load_dwordx4 v[138:141], v178, s[20:21] offset:832
	global_load_dwordx4 v[142:145], v178, s[20:21] offset:864
	global_load_lds_dwordx4 v179, s[36:37]
	s_add_i32 m0, s35, 0x1c00
	global_load_dwordx4 v[146:149], v178, s[20:21] offset:896
	global_load_dwordx4 v[150:153], v178, s[20:21] offset:928
	global_load_dwordx4 v[154:157], v178, s[20:21] offset:960
	global_load_dwordx4 v[158:161], v178, s[20:21] offset:992
	global_load_lds_dwordx4 v180, s[36:37]
	s_branch .Lsg10_issued

.Lsg10_done:
	s_waitcnt lgkmcnt(0)
.LBB10_3:
	s_barrier
	s_cmpk_gt_i32 s2, 0xff
	v_readfirstlane_b32 s13, v0
	s_cbranch_scc1 .LBB10_27
	s_ashr_i32 s30, s2, 31
	s_lshr_b32 s6, s30, 29
	s_add_i32 s10, s2, s6
	s_and_b32 s6, s10, -8
	s_sub_i32 s9, s2, s6
	s_cmp_lt_i32 s9, 0
	s_cbranch_scc1 .LBB10_6
	s_lshl_b32 s8, s9, 5
	s_ashr_i32 s7, s10, 3
	s_cbranch_execz .LBB10_7
	s_branch .LBB10_8

_Z10fwd_kernelILi13ELi14EEv4Args:
	v_mov_b32_e32 v1, v0
	s_load_dword s3, s[0:1], 0xe8
	s_load_dwordx2 s[0:1], s[0:1], 0xd8
	v_readfirstlane_b32 s4, v1
	s_ashr_i32 s6, s4, 6
	s_waitcnt lgkmcnt(0)
	s_add_u32 s4, s0, 0x2900000
	s_addc_u32 s5, s1, 0
	s_add_u32 s20, s0, 0xf400000
	s_addc_u32 s21, s1, 0
	s_add_u32 s22, s0, 0x100000
	s_addc_u32 s23, s1, 0
	v_readfirstlane_b32 s24, v0
	s_lshr_b32 s24, s24, 6
	v_and_b32_e32 v185, 31, v0
	v_bfe_u32 v186, v0, 5, 1
	v_and_b32_e32 v187, 63, v0
	v_lshlrev_b32_e32 v182, 13, v185
	v_lshl_add_u32 v182, v186, 4, v182
	v_lshlrev_b32_e32 v183, 2, v185
	v_lshl_add_u32 v183, v186, 14, v183
	v_lshlrev_b32_e32 v184, 4, v187
	s_mov_b32 s25, s2
	s_cmpk_gt_u32 s25, 0xff
	s_cbranch_scc1 .Lsg13_done
.Lsg13_wg:
	s_and_b32 s26, s25, 7
	s_lshr_b32 s27, s25, 3
	s_mov_b32 s29, s26
	s_lshr_b32 s28, s27, 1
	s_and_b32 s30, s27, 1
	s_lshl_b32 s30, s30, 3
	s_add_u32 s30, s30, s24
	s_lshl_b32 s31, s29, 10
	s_lshl_b32 s33, s28, 19
	s_add_u32 s33, s33, s31
	s_lshl_b32 s34, s24, 7
	s_add_u32 s33, s33, s34
	s_add_u32 s36, s4, s33
	s_addc_u32 s37, s5, 0
	v_mov_b32_e32 v179, v182
	v_add_u32_e32 v180, 0x40000, v182
	s_lshl_b32 s33, s30, 18
	s_add_u32 s33, s33, s31
	v_add_u32_e32 v178, s33, v182
	s_lshl_b32 s33, s29, 21
	s_lshl_b32 s34, s30, 17
	s_add_u32 s33, s33, s34
	s_lshl_b32 s34, s28, 8
	s_add_u32 s33, s33, s34
	v_add_u32_e32 v181, s33, v183
	s_lshl_b32 s35, s24, 13
	s_cmp_lt_u32 s24, 8
	s_cbranch_scc0 .Lsg13_wonly
	s_add_i32 m0, s35, 0x0
	global_load_dwordx4 v[34:37], v178, s[20:21] offset:0
	global_load_dwordx4 v[38:41], v178, s[20:21] offset:32
	global_load_dwordx4 v[42:45], v178, s[20:21] offset:64
	global_load_dwordx4 v[46:49], v178, s[20:21] offset:96
	global_load_lds_dwordx4 v179, s[36:37]
	s_add_i32 m0, s35, 0x400
	global_load_dwordx4 v[50:53], v178, s[20:21] offset:128
	global_load_dwordx4 v[54:57], v178, s[20:21] offset:160
	global_load_dwordx4 v[58:61], v178, s[20:21] offset:192
	global_load_dwordx4 v[62:65], v178, s[20:21] offset:224
	global_load_lds_dwordx4 v180, s[36:37]
	s_add_u32 s36, s36, 32
	s_addc_u32 s37, s37, 0
	s_add_i32 m0, s35, 0x800
	global_load_dwordx4 v[66:69], v178, s[20:21] offset:256
	global_load_dwordx4 v[70:73], v178, s[20:21] offset:288
	global_load_dwordx4 v[74:77], v178, s[20:21] offset:320
	global_load_dwordx4 v[78:81], v178, s[20:21] offset:352
	global_load_lds_dwordx4 v179, s[36:37]
	s_add_i32 m0, s35, 0xc00
	global_load_dwordx4 v[82:85], v178, s[20:21] offset:384
	global_load_dwordx4 v[86:89], v178, s[20:21] offset:416
	global_load_dwordx4 v[90:93], v178, s[20:21] offset:448
	global_load_dwordx4 v[94:97], v178, s[20:21] offset:480
	global_load_lds_dwordx4 v180, s[36:37]
	s_add_u32 s36, s36, 32
	s_addc_u32 s37, s37, 0
	s_add_i32 m0, s35, 0x1000
	global_load_dwordx4 v[98:101], v178, s[20:21] offset:512
	global_load_dwordx4 v[102:105], v178, s[20:21] offset:544
	global_load_dwordx4 v[106:109], v178, s[20:21] offset:576
	global_load_dwordx4 v[110:113], v178, s[20:21] offset:608
	global_load_lds_dwordx4 v179, s[36:37]
	s_add_i32 m0, s35, 0x1400
	global_load_dwordx4 v[114:117], v178, s[20:21] offset:640
	global_load_dwordx4 v[118:121], v178, s[20:21] offset:672
	global_load_dwordx4 v[122:125], v178, s[20:21] offset:704
	global_load_dwordx4 v[126:129], v178, s[20:21] offset:736
	global_load_lds_dwordx4 v180, s[36:37]
	s_add_u32 s36, s36, 32
	s_addc_u32 s37, s37, 0
	s_add_i32 m0, s35, 0x1800
	global_load_dwordx4 v[130:133], v178, s[20:21] offset:768
	global_load_dwordx4 v[134:137], v178, s[20:21] offset:800
	global_load_dwordx4 v[138:141], v178, s[20:21] offset:832
	global_load_dwordx4 v[142:145], v178, s[20:21] offset:864
	global_load_lds_dwordx4 v179, s[36:37]
	s_add_i32 m0, s35, 0x1c00
	global_load_dwordx4 v[146:149], v178, s[20:21] offset:896
	global_load_dwordx4 v[150:153], v178, s[20:21] offset:928
	global_load_dwordx4 v[154:157], v178, s[20:21] offset:960
	global_load_dwordx4 v[158:161], v178, s[20:21] offset:992
	global_load_lds_dwordx4 v180, s[36:37]

.Lsg13_done:
	s_waitcnt lgkmcnt(0)
.LBB13_3:
	s_barrier
	s_cmpk_gt_i32 s2, 0xff
	v_readfirstlane_b32 s13, v0
	s_cbranch_scc1 .LBB13_27
	s_ashr_i32 s30, s2, 31
	s_lshr_b32 s6, s30, 29
	s_add_i32 s10, s2, s6
	s_and_b32 s6, s10, -8
	s_sub_i32 s9, s2, s6
	s_cmp_lt_i32 s9, 0
	s_cbranch_scc1 .LBB13_6
	s_lshl_b32 s8, s9, 5
	s_ashr_i32 s7, s10, 3
	s_cbranch_execz .LBB13_7
	s_branch .LBB13_8
